# one static s_setprio 1 for waves 0-3 at kernel entry
# speedup vs baseline: 1.0035x; 1.0035x over previous
_Z10hybrid_fwd4Args:
	s_mov_b32 s87, s2
	s_load_dwordx2 s[36:37], s[0:1], 0x108
	s_load_dword s2, s[0:1], 0x110
	v_and_b32_e32 v1, 0x3ff, v0
	v_cmp_eq_u32_e32 vcc, 0, v1
	v_readfirstlane_b32 s92, v1
	s_waitcnt lgkmcnt(0)
	s_nop 3
	s_cmp_lt_u32 s92, 0x100
	s_cbranch_scc0 .Lprio_skip
	s_setprio 1
